# P2 stack: hgrn state-update reads 4 deep, attention staging loads issued together, softmax exp arguments in packed form
# baseline (speedup 1.0000x reference)
; __device__ __forceinline__ void attn_item(Frame& F, int item) {
;     ...
;         for (int r = 0; r < 4; ++r) { if (!(l15 < 4 * quad + r)) sc[0][r] = NEG; if (!(l15 >= 4 * quad + r)) sc[8][r] = NEG; }
;         if (qb == 0) {
; #pragma unroll
;             for (int kt = 0; kt < 9; ++kt)
; #pragma unroll
;                 for (int r = 0; r < 4; ++r) if (16 * w + 16 * kt + 4 * quad + r < 128) sc[kt][r] = NEG;
;         }
;         const float sink = F.sinks[qh];
;         float m = sink;
; #pragma unroll
;         for (int kt = 0; kt < 9; ++kt)
; #pragma unroll
;             for (int r = 0; r < 4; ++r) m = fmaxf(m, sc[kt][r]);
;         m = fmaxf(m, __shfl_xor(m, 16)); m = fmaxf(m, __shfl_xor(m, 32));
;         float l = 0.f;
; #pragma unroll
;         for (int kt = 0; kt < 9; ++kt)
; #pragma unroll
;             for (int r = 0; r < 4; ++r) { const float p = __expf(sc[kt][r] - m); sc[kt][r] = p; l += p; }
;         l += __shfl_xor(l, 16); l += __shfl_xor(l, 32);
;         l += __expf(sink - m);
.LBB0_489:
	s_and_b64 vcc, s[10:11], s[8:9]
	s_nop 4
	v_cndmask_b32_e32 v190, v190, v224, vcc
	s_and_b64 vcc, vcc, s[6:7]
	v_cndmask_b32_e32 v189, v189, v224, vcc
	s_and_b64 vcc, vcc, s[4:5]
	v_cndmask_b32_e32 v188, v188, v224, vcc
	v_cndmask_b32_e64 v191, v191, v224, s[10:11]
	s_waitcnt vmcnt(0)
	v_max3_f32 v201, v239, v186, v1
	v_max3_f32 v201, v201, v2, v3
	v_max3_f32 v201, v201, v182, v183
	v_max3_f32 v201, v201, v184, v185
	v_max3_f32 v201, v201, v178, v179
	v_max3_f32 v201, v201, v180, v181
	v_max3_f32 v201, v201, v174, v175
	v_max3_f32 v201, v201, v176, v177
	v_max3_f32 v201, v201, v170, v171
	v_max3_f32 v201, v201, v172, v173
	v_max3_f32 v201, v201, v166, v167
	v_max3_f32 v201, v201, v168, v169
	v_max3_f32 v201, v201, v162, v163
	v_max3_f32 v201, v201, v164, v165
	v_max3_f32 v201, v201, v158, v159
	v_max3_f32 v201, v201, v160, v161
	v_max3_f32 v201, v201, v188, v189
	v_max3_f32 v201, v201, v190, v191
	ds_bpermute_b32 v226, v207, v201
	s_waitcnt lgkmcnt(0)
	v_max_f32_e32 v226, v226, v226
	v_max_f32_e32 v201, v201, v226
	ds_bpermute_b32 v226, v208, v201
	s_waitcnt lgkmcnt(0)
	v_max_f32_e32 v226, v226, v226
	v_max_f32_e32 v201, v201, v226
	v_mov_b32_e32 v240, v201
	v_mov_b32_e32 v242, 0x3fb8aa3b
	v_sub_f32_e32 v186, v186, v201
	v_sub_f32_e32 v1, v1, v201
	v_pk_add_f32 v[2:3], v[2:3], v[240:241] op_sel_hi:[1,0] neg_lo:[0,1] neg_hi:[0,1]
	v_pk_add_f32 v[182:183], v[182:183], v[240:241] op_sel_hi:[1,0] neg_lo:[0,1] neg_hi:[0,1]
	v_pk_add_f32 v[184:185], v[184:185], v[240:241] op_sel_hi:[1,0] neg_lo:[0,1] neg_hi:[0,1]
	v_pk_add_f32 v[178:179], v[178:179], v[240:241] op_sel_hi:[1,0] neg_lo:[0,1] neg_hi:[0,1]
	v_pk_add_f32 v[180:181], v[180:181], v[240:241] op_sel_hi:[1,0] neg_lo:[0,1] neg_hi:[0,1]
	v_pk_add_f32 v[174:175], v[174:175], v[240:241] op_sel_hi:[1,0] neg_lo:[0,1] neg_hi:[0,1]
	v_pk_add_f32 v[176:177], v[176:177], v[240:241] op_sel_hi:[1,0] neg_lo:[0,1] neg_hi:[0,1]
	v_pk_add_f32 v[170:171], v[170:171], v[240:241] op_sel_hi:[1,0] neg_lo:[0,1] neg_hi:[0,1]
	v_pk_add_f32 v[172:173], v[172:173], v[240:241] op_sel_hi:[1,0] neg_lo:[0,1] neg_hi:[0,1]
	v_pk_add_f32 v[166:167], v[166:167], v[240:241] op_sel_hi:[1,0] neg_lo:[0,1] neg_hi:[0,1]
	v_pk_add_f32 v[168:169], v[168:169], v[240:241] op_sel_hi:[1,0] neg_lo:[0,1] neg_hi:[0,1]
	v_pk_add_f32 v[162:163], v[162:163], v[240:241] op_sel_hi:[1,0] neg_lo:[0,1] neg_hi:[0,1]
	v_pk_add_f32 v[164:165], v[164:165], v[240:241] op_sel_hi:[1,0] neg_lo:[0,1] neg_hi:[0,1]
	v_pk_add_f32 v[158:159], v[158:159], v[240:241] op_sel_hi:[1,0] neg_lo:[0,1] neg_hi:[0,1]
	v_pk_add_f32 v[160:161], v[160:161], v[240:241] op_sel_hi:[1,0] neg_lo:[0,1] neg_hi:[0,1]
	v_pk_add_f32 v[188:189], v[188:189], v[240:241] op_sel_hi:[1,0] neg_lo:[0,1] neg_hi:[0,1]
	v_pk_add_f32 v[190:191], v[190:191], v[240:241] op_sel_hi:[1,0] neg_lo:[0,1] neg_hi:[0,1]
	v_mul_f32_e32 v186, 0x3fb8aa3b, v186
	v_mul_f32_e32 v1, 0x3fb8aa3b, v1
	v_pk_mul_f32 v[2:3], v[2:3], v[242:243] op_sel_hi:[1,0]
	v_pk_mul_f32 v[182:183], v[182:183], v[242:243] op_sel_hi:[1,0]
	v_pk_mul_f32 v[184:185], v[184:185], v[242:243] op_sel_hi:[1,0]
	v_pk_mul_f32 v[178:179], v[178:179], v[242:243] op_sel_hi:[1,0]
	v_pk_mul_f32 v[180:181], v[180:181], v[242:243] op_sel_hi:[1,0]
	v_pk_mul_f32 v[174:175], v[174:175], v[242:243] op_sel_hi:[1,0]
	v_pk_mul_f32 v[176:177], v[176:177], v[242:243] op_sel_hi:[1,0]
	v_pk_mul_f32 v[170:171], v[170:171], v[242:243] op_sel_hi:[1,0]
	v_pk_mul_f32 v[172:173], v[172:173], v[242:243] op_sel_hi:[1,0]
	v_pk_mul_f32 v[166:167], v[166:167], v[242:243] op_sel_hi:[1,0]
	v_pk_mul_f32 v[168:169], v[168:169], v[242:243] op_sel_hi:[1,0]
	v_pk_mul_f32 v[162:163], v[162:163], v[242:243] op_sel_hi:[1,0]
	v_pk_mul_f32 v[164:165], v[164:165], v[242:243] op_sel_hi:[1,0]
	v_pk_mul_f32 v[158:159], v[158:159], v[242:243] op_sel_hi:[1,0]
	v_pk_mul_f32 v[160:161], v[160:161], v[242:243] op_sel_hi:[1,0]
	v_pk_mul_f32 v[188:189], v[188:189], v[242:243] op_sel_hi:[1,0]
	v_pk_mul_f32 v[190:191], v[190:191], v[242:243] op_sel_hi:[1,0]
	v_exp_f32_e32 v186, v186
	v_exp_f32_e32 v1, v1
	v_exp_f32_e32 v2, v2
	v_exp_f32_e32 v3, v3
	v_exp_f32_e32 v182, v182
	v_exp_f32_e32 v183, v183
	v_exp_f32_e32 v184, v184
	v_exp_f32_e32 v185, v185
	v_exp_f32_e32 v178, v178
	v_exp_f32_e32 v179, v179
	v_exp_f32_e32 v180, v180
	v_exp_f32_e32 v181, v181
	v_exp_f32_e32 v174, v174
	v_exp_f32_e32 v175, v175
	v_exp_f32_e32 v176, v176
	v_exp_f32_e32 v177, v177
	v_exp_f32_e32 v170, v170
	v_exp_f32_e32 v171, v171
	v_exp_f32_e32 v172, v172
	v_exp_f32_e32 v173, v173
	v_exp_f32_e32 v226, v166
	v_exp_f32_e32 v227, v167
	v_exp_f32_e32 v228, v168
	v_exp_f32_e32 v229, v169
	v_exp_f32_e32 v230, v162
	v_exp_f32_e32 v231, v163
	v_exp_f32_e32 v232, v164
	v_exp_f32_e32 v233, v165
	v_exp_f32_e32 v234, v158
	v_exp_f32_e32 v235, v159
	v_exp_f32_e32 v236, v160
	v_exp_f32_e32 v237, v161
	v_exp_f32_e32 v188, v188
	v_exp_f32_e32 v189, v189
	v_exp_f32_e32 v190, v190
	v_exp_f32_e32 v191, v191
	v_add_f32_e32 v162, 0, v186
	v_add_f32_e32 v162, v1, v162
	v_add_f32_e32 v162, v2, v162
	v_add_f32_e32 v162, v3, v162
	v_add_f32_e32 v162, v182, v162
	v_add_f32_e32 v162, v183, v162
	v_add_f32_e32 v162, v184, v162
	v_add_f32_e32 v162, v185, v162
	v_add_f32_e32 v162, v178, v162
	v_add_f32_e32 v162, v179, v162
	v_add_f32_e32 v162, v180, v162
	v_add_f32_e32 v162, v181, v162
	v_add_f32_e32 v162, v174, v162
	v_add_f32_e32 v162, v175, v162
	v_add_f32_e32 v162, v176, v162
	v_add_f32_e32 v162, v177, v162
	v_add_f32_e32 v162, v170, v162
	v_add_f32_e32 v162, v171, v162
	v_add_f32_e32 v162, v172, v162
	v_add_f32_e32 v162, v173, v162
	v_add_f32_e32 v162, v226, v162
	v_add_f32_e32 v162, v227, v162
	v_add_f32_e32 v162, v228, v162
	v_add_f32_e32 v162, v229, v162
	v_add_f32_e32 v162, v230, v162
	v_add_f32_e32 v162, v231, v162
	v_add_f32_e32 v162, v232, v162
	v_add_f32_e32 v162, v233, v162
	v_add_f32_e32 v158, v234, v162
	v_add_f32_e32 v158, v235, v158
	v_add_f32_e32 v158, v236, v158
	v_add_f32_e32 v158, v237, v158
	v_add_f32_e32 v158, v188, v158
	v_add_f32_e32 v158, v189, v158
	v_add_f32_e32 v158, v190, v158
	v_add_f32_e32 v158, v191, v158
	ds_bpermute_b32 v159, v207, v158
	v_sub_f32_e32 v5, v239, v201
	v_mul_f32_e32 v5, 0x3fb8aa3b, v5
	v_exp_f32_e32 v5, v5
	v_cvt_pk_bf16_f32 v160, v182, v183
	s_waitcnt lgkmcnt(0)
; #define LAS __attribute__((address_space(3)))
; __device__ __forceinline__ unsigned pk2(float lo, float hi) { return f2bf(lo) | (f2bf(hi) << 16); }
; #define MFMA16(a, b, c) __builtin_amdgcn_mfma_f32_16x16x32_bf16((a), (b), (c), 0, 0, 0)
; __device__ __forceinline__ void attn_item(Frame& F, int item) {
;     ...
;         l += __shfl_xor(l, 16); l += __shfl_xor(l, 32);
;         l += __expf(sink - m);
;         const float il = __builtin_amdgcn_rcpf(l);
;         bf16x8 pf[5];
; #pragma unroll
;         for (int kk = 0; kk < 4; ++kk) pf[kk] = pack8(sc[2 * kk], sc[2 * kk + 1]);
;         pf[4] = pack8(sc[8], (f32x4){0.f, 0.f, 0.f, 0.f});
; #pragma unroll
;         for (int dt = 0; dt < 4; ++dt) {
;             f32x4 o = (f32x4){0.f, 0.f, 0.f, 0.f};
;             const LAS bf16* vrow = Vt + (16 * dt + l15) * VT2_STRIDE + 16 * w + 4 * quad;
; #pragma unroll
;             for (int kk = 0; kk < 5; ++kk) {
;                 const v2u lo = *(const LAS v2u*)(vrow + 32 * kk);
;                 v2u hi = (v2u){0u, 0u}; if (kk < 4) hi = *(const LAS v2u*)(vrow + 32 * kk + 16);
;                 o = MFMA16(join8(lo, hi), pf[kk], o);
;             }
;             v2u ow; ow.x = pk2(o[0] * il, o[1] * il); ow.y = pk2(o[2] * il, o[3] * il);
;             *(v2u*)(F.MIXED + row * D + 512 + qh * 64 + 16 * dt + 4 * quad) = ow;
;         }
	v_add_f32_e32 v158, v158, v159
	ds_bpermute_b32 v159, v208, v158
	v_cvt_pk_bf16_f32 v161, v184, v185
	v_cvt_pk_bf16_f32 v162, v178, v179
	v_cvt_pk_bf16_f32 v163, v180, v181
	v_cvt_pk_bf16_f32 v164, v174, v175
	s_waitcnt lgkmcnt(0)
	v_add_f32_e32 v158, v158, v159
	v_add_f32_e32 v5, v5, v158
	v_cvt_pk_bf16_f32 v158, v186, v1
	v_cvt_pk_bf16_f32 v159, v2, v3
	v_cvt_pk_bf16_f32 v165, v176, v177
	v_cvt_pk_bf16_f32 v170, v170, v171
	v_mfma_f32_16x16x32_bf16 v[166:169], v[78:81], v[158:161], 0
	v_cvt_pk_bf16_f32 v171, v172, v173
	v_cvt_pk_bf16_f32 v172, v226, v227
	v_cvt_pk_bf16_f32 v173, v228, v229
	v_mfma_f32_16x16x32_bf16 v[166:169], v[82:85], v[162:165], v[166:169]
	v_cvt_pk_bf16_f32 v174, v230, v231
	v_cvt_pk_bf16_f32 v175, v232, v233
	v_cvt_pk_bf16_f32 v176, v234, v235
	v_mfma_f32_16x16x32_bf16 v[166:169], v[86:89], v[170:173], v[166:169]
	v_cvt_pk_bf16_f32 v177, v236, v237
	v_rcp_f32_e32 v178, v5
	v_cvt_pk_bf16_f32 v2, v188, v189
	v_mfma_f32_16x16x32_bf16 v[166:169], v[90:93], v[174:177], v[166:169]
	v_cvt_pk_bf16_f32 v3, v190, v191
	v_mov_b32_e32 v5, v4
	s_nop 1
	v_mfma_f32_16x16x32_bf16 v[166:169], v[94:97], v[2:5], v[166:169]
	s_nop 7
	v_mov_b32_e32 v181, v168
	v_mov_b32_e32 v168, v167
	v_mov_b32_e32 v180, v166
	v_pk_mul_f32 v[182:183], v[168:169], v[178:179] op_sel_hi:[1,0]
	v_mfma_f32_16x16x32_bf16 v[166:169], v[98:101], v[158:161], 0
	v_mul_f32_e64 v180, v180, v178
	v_mul_f32_e64 v181, v181, v178
	v_and_b32_sdwa v1, v181, v225 dst_sel:DWORD dst_unused:UNUSED_PAD src0_sel:WORD_1 src1_sel:DWORD
	v_mfma_f32_16x16x32_bf16 v[166:169], v[102:105], v[162:165], v[166:169]
	v_and_b32_sdwa v179, v180, v225 dst_sel:DWORD dst_unused:UNUSED_PAD src0_sel:WORD_1 src1_sel:DWORD
	v_add3_u32 v179, v180, v179, s66
	v_add3_u32 v1, v181, v1, s66
	v_mfma_f32_16x16x32_bf16 v[166:169], v[106:109], v[170:173], v[166:169]
	v_and_b32_sdwa v180, v183, v225 dst_sel:DWORD dst_unused:UNUSED_PAD src0_sel:WORD_1 src1_sel:DWORD
	v_and_b32_sdwa v181, v182, v225 dst_sel:DWORD dst_unused:UNUSED_PAD src0_sel:WORD_1 src1_sel:DWORD
	v_add3_u32 v180, v183, v180, s66
	v_mfma_f32_16x16x32_bf16 v[166:169], v[110:113], v[174:177], v[166:169]
	v_add3_u32 v181, v182, v181, s66
	v_and_b32_e32 v180, 0xffff0000, v180
	v_and_b32_e32 v182, 0xffff0000, v181
	v_mfma_f32_16x16x32_bf16 v[166:169], v[114:117], v[2:5], v[166:169]
	v_or_b32_sdwa v181, v180, v1 dst_sel:DWORD dst_unused:UNUSED_PAD src0_sel:DWORD src1_sel:WORD_1
	v_or_b32_sdwa v180, v182, v179 dst_sel:DWORD dst_unused:UNUSED_PAD src0_sel:DWORD src1_sel:WORD_1
	v_lshl_add_u64 v[182:183], v[204:205], 0, s[82:83]
	global_store_dwordx2 v[182:183], v[180:181], off offset:-64
	s_add_u32 s82, s82, 0x80
	s_nop 2
	v_mov_b32_e32 v181, v168
	v_mov_b32_e32 v168, v167
	v_mov_b32_e32 v180, v166
	v_pk_mul_f32 v[184:185], v[168:169], v[178:179] op_sel_hi:[1,0]
	v_mfma_f32_16x16x32_bf16 v[166:169], v[118:121], v[158:161], 0
	v_mul_f32_e64 v180, v180, v178
	v_mul_f32_e64 v181, v181, v178
	s_addc_u32 s83, s83, 0
	v_and_b32_sdwa v1, v181, v225 dst_sel:DWORD dst_unused:UNUSED_PAD src0_sel:WORD_1 src1_sel:DWORD
	v_mfma_f32_16x16x32_bf16 v[158:161], v[138:141], v[158:161], 0
	v_and_b32_sdwa v179, v180, v225 dst_sel:DWORD dst_unused:UNUSED_PAD src0_sel:WORD_1 src1_sel:DWORD
	v_add3_u32 v179, v180, v179, s66
	v_add3_u32 v1, v181, v1, s66
	v_mfma_f32_16x16x32_bf16 v[166:169], v[122:125], v[162:165], v[166:169]
	v_and_b32_sdwa v180, v185, v225 dst_sel:DWORD dst_unused:UNUSED_PAD src0_sel:WORD_1 src1_sel:DWORD
	v_and_b32_sdwa v181, v184, v225 dst_sel:DWORD dst_unused:UNUSED_PAD src0_sel:WORD_1 src1_sel:DWORD
	v_add3_u32 v180, v185, v180, s66
	v_mfma_f32_16x16x32_bf16 v[158:161], v[142:145], v[162:165], v[158:161]
	v_add3_u32 v181, v184, v181, s66
	v_and_b32_e32 v180, 0xffff0000, v180
	v_and_b32_e32 v184, 0xffff0000, v181
	v_mfma_f32_16x16x32_bf16 v[166:169], v[126:129], v[170:173], v[166:169]
	v_or_b32_sdwa v181, v180, v1 dst_sel:DWORD dst_unused:UNUSED_PAD src0_sel:DWORD src1_sel:WORD_1
	v_or_b32_sdwa v180, v184, v179 dst_sel:DWORD dst_unused:UNUSED_PAD src0_sel:DWORD src1_sel:WORD_1
	global_store_dwordx2 v[182:183], v[180:181], off offset:-32
	v_mfma_f32_16x16x32_bf16 v[158:161], v[146:149], v[170:173], v[158:161]
	s_add_u32 s78, s78, 4
	s_addc_u32 s79, s79, 0
	s_cmpk_lg_i32 s82, 0x200
	v_mfma_f32_16x16x32_bf16 v[166:169], v[130:133], v[174:177], v[166:169]
	v_mfma_f32_16x16x32_bf16 v[158:161], v[150:153], v[174:177], v[158:161]
	v_mfma_f32_16x16x32_bf16 v[166:169], v[134:137], v[2:5], v[166:169]
	v_mfma_f32_16x16x32_bf16 v[158:161], v[154:157], v[2:5], v[158:161]
	s_nop 6
	v_mov_b32_e32 v181, v168
	v_mov_b32_e32 v168, v167
	v_mov_b32_e32 v180, v166
	v_pk_mul_f32 v[166:167], v[168:169], v[178:179] op_sel_hi:[1,0]
	v_pk_mul_f32 v[180:181], v[180:181], v[178:179] op_sel_hi:[1,0]
	v_and_b32_sdwa v163, v166, v225 dst_sel:DWORD dst_unused:UNUSED_PAD src0_sel:WORD_1 src1_sel:DWORD
	v_mov_b32_e32 v2, v158
	v_mov_b32_e32 v3, v160
	v_add3_u32 v163, v166, v163, s66
	v_pk_mul_f32 v[2:3], v[2:3], v[178:179] op_sel_hi:[1,0]
	v_mov_b32_e32 v160, v159
	v_and_b32_e32 v164, 0xffff0000, v163
	v_cvt_pk_bf16_f32 v163, v181, v167
	v_pk_mul_f32 v[158:159], v[160:161], v[178:179] op_sel_hi:[1,0]
	v_and_b32_sdwa v168, v180, v225 dst_sel:DWORD dst_unused:UNUSED_PAD src0_sel:WORD_1 src1_sel:DWORD
	v_add3_u32 v168, v180, v168, s66
	v_or_b32_sdwa v162, v164, v168 dst_sel:DWORD dst_unused:UNUSED_PAD src0_sel:DWORD src1_sel:WORD_1
	v_cvt_pk_bf16_f32 v3, v3, v159
	v_cvt_pk_bf16_f32 v2, v2, v158
	global_store_dwordx2 v[182:183], v[162:163], off
	global_store_dwordx2 v[182:183], v[2:3], off offset:32
	s_cbranch_scc0 .LBB0_485
